# adds RWKV latency edits: phase-B latch does not wait for post-chunk stores; phase-A parameter loads as global loads, one wait before the 8-step loop
# baseline (speedup 1.0000x reference)
; __device__ __forceinline__ float bf2f(bf16_t v) { return __uint_as_float(((unsigned)v) << 16); }
; #define RW_LD8(dst, t8_) do { const unsigned ul = launder_(ul0); _Pragma("unroll") for (int tt = 0; tt < 8; ++tt) { const bf16_t* p = pb + (size_t)(8 * (t8_) + tt) * IN_EVEN_P; const bf16_t* lo = lb + (size_t)(8 * (t8_) + tt) * 1536; \
;             dst[tt][0] = p[ul]; dst[tt][1] = p[512 + ul]; dst[tt][2] = p[1024 + ul]; dst[tt][3] = lo[ul]; dst[tt][4] = lo[512 + ul]; } } while (0)
; __device__ __forceinline__ void rwkv_phaseA(const Ctx& F, LAS unsigned char* W, unsigned char* X, int b, int h, int c) {
;     ...
;     const float mu_r = F_mu[col], mu_k = F_mu[512 + col], mu_v = F_mu[1024 + col], w0 = F_w0[col], a0 = F_a0[col], k_k = F_k_k[col], k_a = F_k_a[col], r_k = F_r_k[col];
;     float Bc = 0.f, cprev = 1.f;
;     {
;         const unsigned ul0 = (unsigned)lane;
;         const size_t row0 = (size_t)b * S + c * 32;
;         const bf16_t* pb = proj + row0 * IN_EVEN_P + RW_OFF + h * 64; const bf16_t* lb = LO + row0 * 1536 + h * 64;
;         float pr_ = 0.f, pk_ = 0.f, pv_ = 0.f;
;         if (c > 0) { const bf16_t* pp = pb - IN_EVEN_P; pr_ = bf2f(pp[ul0]); pk_ = bf2f(pp[512 + ul0]); pv_ = bf2f(pp[1024 + ul0]); }
;         bf16_t cur[8][5], nxt[8][5];
;     ...
;         RW_LD8(cur, 0);
.LBB0_792:
	s_andn2_b64 vcc, exec, s[16:17]
	s_waitcnt vmcnt(0) lgkmcnt(0)
	s_barrier
	s_cbranch_vccnz .LBB0_833
	v_mbcnt_lo_u32_b32 v2, -1, 0
	v_mbcnt_hi_u32_b32 v2, -1, v2
	s_load_dwordx2 s[8:9], s[12:13], 0x68
	v_add_u32_e32 v12, s14, v2
	v_ashrrev_i32_e32 v13, 31, v12
	v_lshlrev_b64 v[12:13], 2, v[12:13]
	v_lshl_add_u64 v[14:15], s[36:37], 0, v[12:13]
	v_add_co_u32_e32 v16, vcc, 0x1000, v14
	s_nop 1
	v_addc_co_u32_e32 v17, vcc, 0, v15, vcc
	global_load_dword v20, v[14:15], off
	global_load_dword v21, v[14:15], off offset:2048
	global_load_dword v22, v[16:17], off
	s_load_dwordx2 s[10:11], s[12:13], 0x78
	s_load_dwordx4 s[4:7], s[12:13], 0x90
	s_load_dwordx2 s[60:61], s[12:13], 0xa0
	s_waitcnt lgkmcnt(0)
	v_lshl_add_u64 v[14:15], s[8:9], 0, v[12:13]
	global_load_dword v23, v[14:15], off
	v_lshl_add_u64 v[14:15], s[10:11], 0, v[12:13]
	global_load_dword v24, v[14:15], off
	v_lshl_add_u64 v[14:15], s[4:5], 0, v[12:13]
	global_load_dword v25, v[14:15], off
	v_lshl_add_u64 v[14:15], s[6:7], 0, v[12:13]
	v_lshl_add_u64 v[12:13], s[60:61], 0, v[12:13]
	global_load_dword v26, v[14:15], off
	global_load_dword v27, v[12:13], off
	s_lshl_b32 s4, s22, 2
	s_or_b32 s8, s4, s50
	s_lshl_b32 s4, s8, 5
	s_add_u32 s6, s38, s4
	s_addc_u32 s7, s39, 0
	s_mul_i32 s4, s7, 0x1400
	s_mul_hi_u32 s5, s6, 0x1400
	s_add_i32 s5, s5, s4
	s_mul_i32 s4, s6, 0x1400
	s_add_u32 s4, s46, s4
	s_addc_u32 s5, s47, s5
	s_lshl_b32 s9, s14, 1
	s_add_u32 s4, s4, s9
	s_addc_u32 s5, s5, 0
	s_add_u32 s4, s4, 0xc200540
	s_addc_u32 s5, s5, 0
	s_cmp_eq_u32 s8, 0
	s_cbranch_scc1 .LBB0_795
	s_add_u32 s8, s4, 0xffffec00
	s_addc_u32 s9, s5, -1
	v_mov_b32_e32 v3, v1
	v_add_u32_e32 v0, 0x200, v2
	v_lshl_add_u64 v[12:13], v[2:3], 1, s[8:9]
	v_lshl_add_u64 v[14:15], v[0:1], 1, s[8:9]
	v_add_u32_e32 v0, 0x400, v2
	v_lshl_add_u64 v[16:17], v[0:1], 1, s[8:9]
	global_load_ushort v150, v[14:15], off
	global_load_ushort v151, v[16:17], off
	global_load_ushort v152, v[12:13], off
	s_branch .LBB0_796
.LBB0_795:
	v_mov_b32_e32 v150, 0
	v_mov_b32_e32 v151, 0
	v_mov_b32_e32 v152, 0
.LBB0_796:
	s_mulk_i32 s7, 0xc00
	s_mul_hi_u32 s8, s6, 0xc00
	s_add_i32 s8, s8, s7
	s_mulk_i32 s6, 0xc00
	s_add_u32 s6, s15, s6
	s_addc_u32 s7, s70, s8
	v_mov_b32_e32 v0, v2
	v_mov_b32_e32 v17, v1
	v_add_u32_e32 v16, 0x200, v0
	v_add_u32_e32 v18, 0x400, v0
	v_mov_b32_e32 v19, v1
	s_add_u32 s8, s4, 0x1400
	v_lshlrev_b64 v[14:15], 1, v[0:1]
	v_lshlrev_b64 v[16:17], 1, v[16:17]
	v_lshlrev_b64 v[18:19], 1, v[18:19]
	s_addc_u32 s9, s5, 0
	v_lshl_add_u64 v[38:39], s[8:9], 0, v[14:15]
	v_lshl_add_u64 v[40:41], s[8:9], 0, v[16:17]
	v_lshl_add_u64 v[42:43], s[8:9], 0, v[18:19]
	s_add_u32 s8, s4, 0x2800
	s_addc_u32 s9, s5, 0
	s_add_u32 s10, s6, 0x1800
	v_lshl_add_u64 v[28:29], s[4:5], 0, v[14:15]
	v_lshl_add_u64 v[30:31], s[4:5], 0, v[16:17]
	v_lshl_add_u64 v[34:35], s[6:7], 0, v[14:15]
	v_lshl_add_u64 v[36:37], s[6:7], 0, v[16:17]
	s_addc_u32 s11, s7, 0
	v_lshl_add_u64 v[32:33], s[4:5], 0, v[18:19]
	global_load_ushort v0, v[28:29], off
	s_nop 0
	global_load_ushort v29, v[30:31], off
	global_load_ushort v28, v[32:33], off
	s_nop 0
	global_load_ushort v30, v[34:35], off
	global_load_ushort v31, v[36:37], off
	global_load_ushort v129, v[38:39], off
	global_load_ushort v130, v[36:37], off offset:3072
	global_load_ushort v131, v[34:35], off offset:3072
	v_lshl_add_u64 v[34:35], s[8:9], 0, v[14:15]
	v_lshl_add_u64 v[36:37], s[8:9], 0, v[16:17]
	v_lshl_add_u64 v[38:39], s[8:9], 0, v[18:19]
	s_add_u32 s8, s4, 0x3c00
	s_addc_u32 s9, s5, 0
	v_lshl_add_u64 v[44:45], s[10:11], 0, v[14:15]
	v_lshl_add_u64 v[46:47], s[10:11], 0, v[16:17]
	s_add_u32 s10, s6, 0x2400
	s_addc_u32 s11, s7, 0
	v_lshl_add_u64 v[48:49], s[8:9], 0, v[14:15]
	global_load_ushort v132, v[40:41], off
	global_load_ushort v32, v[42:43], off
	global_load_ushort v126, v[34:35], off
	global_load_ushort v128, v[36:37], off
	global_load_ushort v33, v[38:39], off
	global_load_ushort v127, v[44:45], off
	global_load_ushort v123, v[46:47], off
	global_load_ushort v119, v[48:49], off
	v_lshl_add_u64 v[34:35], s[8:9], 0, v[16:17]
	v_lshl_add_u64 v[36:37], s[8:9], 0, v[18:19]
	s_add_u32 s8, s4, 0x5000
	s_addc_u32 s9, s5, 0
	v_lshl_add_u64 v[38:39], s[10:11], 0, v[14:15]
	v_lshl_add_u64 v[40:41], s[10:11], 0, v[16:17]
	s_add_u32 s10, s6, 0x3000
	s_addc_u32 s11, s7, 0
	v_lshl_add_u64 v[42:43], s[8:9], 0, v[14:15]
	v_lshl_add_u64 v[44:45], s[8:9], 0, v[16:17]
	v_lshl_add_u64 v[46:47], s[8:9], 0, v[18:19]
	s_add_u32 s8, s4, 0x6400
	s_addc_u32 s9, s5, 0
	v_lshl_add_u64 v[48:49], s[10:11], 0, v[14:15]
	global_load_ushort v122, v[34:35], off
	s_nop 0
	global_load_ushort v34, v[36:37], off
	global_load_ushort v121, v[38:39], off
	global_load_ushort v120, v[40:41], off
	global_load_ushort v107, v[42:43], off
	global_load_ushort v108, v[44:45], off
	global_load_ushort v35, v[46:47], off
	global_load_ushort v109, v[48:49], off
	v_lshl_add_u64 v[36:37], s[10:11], 0, v[16:17]
	s_add_u32 s10, s6, 0x3c00
	s_addc_u32 s11, s7, 0
	v_lshl_add_u64 v[38:39], s[8:9], 0, v[14:15]
	v_lshl_add_u64 v[40:41], s[8:9], 0, v[16:17]
	v_lshl_add_u64 v[42:43], s[8:9], 0, v[18:19]
	s_add_u32 s8, s4, 0x7800
	s_addc_u32 s9, s5, 0
	v_lshl_add_u64 v[44:45], s[10:11], 0, v[14:15]
	v_lshl_add_u64 v[46:47], s[10:11], 0, v[16:17]
	s_add_u32 s10, s6, 0x4800
	s_addc_u32 s11, s7, 0
	v_lshl_add_u64 v[48:49], s[8:9], 0, v[14:15]
	v_lshl_add_u64 v[52:53], s[8:9], 0, v[16:17]
	global_load_ushort v118, v[36:37], off
	global_load_ushort v103, v[38:39], off
	global_load_ushort v105, v[40:41], off
	s_nop 0
	global_load_ushort v39, v[42:43], off
	global_load_ushort v104, v[44:45], off
	global_load_ushort v95, v[46:47], off
	global_load_ushort v50, v[48:49], off
	global_load_ushort v51, v[52:53], off
	v_lshl_add_u64 v[36:37], s[8:9], 0, v[18:19]
	s_add_u32 s8, s4, 0x8c00
	s_addc_u32 s9, s5, 0
	v_lshl_add_u64 v[42:43], s[10:11], 0, v[14:15]
	v_lshl_add_u64 v[44:45], s[10:11], 0, v[16:17]
	s_add_u32 s10, s6, 0x5400
	s_addc_u32 s11, s7, 0
	v_lshl_add_u64 v[40:41], s[8:9], 0, v[14:15]
	v_lshl_add_u64 v[46:47], s[8:9], 0, v[16:17]
	global_load_ushort v38, v[40:41], off
	s_nop 0
	global_load_ushort v46, v[46:47], off
	v_lshl_add_u64 v[18:19], s[8:9], 0, v[18:19]
	v_lshl_add_u64 v[14:15], s[10:11], 0, v[14:15]
	v_lshl_add_u64 v[16:17], s[10:11], 0, v[16:17]
	global_load_ushort v40, v[36:37], off
	global_load_ushort v94, v[42:43], off
	global_load_ushort v67, v[44:45], off
	global_load_ushort v41, v[18:19], off
	global_load_ushort v48, v[14:15], off
	s_nop 0
	global_load_ushort v44, v[16:17], off
	v_mul_lo_u32 v14, v2, s96
	v_lshl_add_u32 v36, v2, 1, s43
	v_cmp_eq_u32_e32 vcc, 0, v2
	v_add_u32_e32 v37, s93, v14
	v_mov_b32_e32 v133, 1.0
	s_mov_b64 s[8:9], 0
	s_mov_b64 s[10:11], 0x30204800
	s_mov_b32 s23, 8
	s_waitcnt vmcnt(0)
	v_lshlrev_b32_e32 v13, 16, v150
	v_lshlrev_b32_e32 v3, 16, v151
	v_lshlrev_b32_e32 v12, 16, v152
	v_perm_b32 v43, v46, v38, s97
	v_mov_b32_e32 v38, 0

; #define LAS __attribute__((address_space(3)))
; __device__ __forceinline__ unsigned launder_(unsigned x) { asm volatile("" : "+v"(x)); return x; }
; __device__ __forceinline__ void rwkv_chunked_bh(const Ctx& F, int b, int h) {
;     ...
;         for (int cc = 0; cc < RG; ++cc) {
;             const int c = grp * RG + cc; const unsigned char* X = XS + cc * RX_BYTES;
;             LAS unsigned char* const Ls = L + (cc & 1) * RBSTG;
;             bf16x8 ng[2][2], hf[2], qf[2], wyf, vf; f32x4 c4[2];
;             const unsigned o128 = launder_((unsigned)(i * 128 + 16 * g)), o64 = launder_((unsigned)(i * 64 + 16 * g)), ulane = launder_((unsigned)lane);
; #pragma unroll
;             for (int q = 0; q < 2; ++q) { const int kt = 2 * kh + q;
;                 ng[q][0] = glb16(X + RX_NGT + 16 * kt * 128 + o128); ng[q][1] = glb16(X + RX_NGT + 16 * kt * 128 + 64 + o128);
;                 hf[q] = glb16(X + RX_HT + 16 * kt * 64 + o64); c4[q] = *(const f32x4*)(X + RX_CC + 16 * kt * 4 + (unsigned)(16 * g)); }
;             qf[0] = glb16(X + RX_QT + 16 * kh * 128 + o128); qf[1] = glb16(X + RX_QT + 16 * kh * 128 + 64 + o128);
;             wyf = glb16(X + RX_WYT + 16 * kh * 64 + o64); vf = glb16(X + RX_VT + 16 * vt * 64 + o64);
;             RwkvPostIn cur;
; #pragma unroll
;             for (int j = 0; j < 4; ++j) { const int t = c * 32 + w + 8 * j; const size_t row = (size_t)b * S + t; const bf16_t* p = proj + row * IN_EVEN_P + RW_OFF + 1024 + h * 64; const unsigned ul = ulane;
;                 cur.pv0[j] = p[ul]; cur.pv1[j] = t > 0 ? (p - IN_EVEN_P)[ul] : (bf16_t)0; cur.gq[j] = (LO + row * 1536 + 1024 + h * 64)[ul]; cur.bon[j] = *(const float*)(X + RX_BON + 4 * (w + 8 * j)); }
.Lrw_top2:
	s_add_u32 s4, s46, s60
	v_mov_b32_e32 v0, v75
	s_addc_u32 s5, s47, s61
	v_mov_b32_e32 v56, v76
	v_lshl_add_u64 v[20:21], s[4:5], 0, v[0:1]
	v_add_co_u32_e32 v16, vcc, s0, v20
	s_add_u32 s4, s46, s62
	v_mov_b32_e32 v57, v1
	v_addc_co_u32_e32 v17, vcc, 0, v21, vcc
	s_addc_u32 s5, s47, s63
	s_mov_b32 vcc_lo, 0x30203000
	v_lshl_add_u64 v[22:23], s[4:5], 0, v[56:57]
	v_add_co_u32_e32 v28, vcc, vcc_lo, v22
	v_lshl_add_u64 v[44:45], s[4:5], 0, v[0:1]
	s_nop 0
	v_addc_co_u32_e32 v29, vcc, 0, v23, vcc
	v_lshl_add_u64 v[22:23], s[46:47], 0, v[2:3]
	s_mov_b32 vcc_lo, 0x30205000
	v_add_co_u32_e32 v36, vcc, vcc_lo, v22
	s_add_u32 s4, s46, s10
	s_nop 0
	v_addc_co_u32_e32 v37, vcc, 0, v23, vcc
	s_mov_b32 vcc_lo, 0x30202000
	s_nop 0
	v_add_co_u32_e32 v24, vcc, vcc_lo, v20
	s_addc_u32 s5, s47, s11
	s_nop 0
	v_addc_co_u32_e32 v25, vcc, 0, v21, vcc
	v_add_co_u32_e32 v44, vcc, s1, v44
	v_mov_b32_e32 v58, v71
	s_nop 0
	v_addc_co_u32_e32 v45, vcc, 0, v45, vcc
	s_add_u32 vcc_lo, s46, s8
	s_addc_u32 vcc_hi, s47, s9
	global_load_dwordx4 v[12:15], v[16:17], off offset:2048
	s_nop 0
	global_load_dwordx4 v[16:19], v[16:17], off offset:2112
	s_nop 0
	global_load_dwordx4 v[20:23], v[24:25], off
	s_nop 0
	global_load_dwordx4 v[24:27], v[24:25], off offset:64
	s_nop 0
	global_load_dwordx4 v[32:35], v[28:29], off offset:2048
	s_nop 0
	global_load_dwordx4 v[28:31], v[28:29], off offset:3072
	s_nop 0
	global_load_dwordx4 v[40:43], v[36:37], off offset:2048
	s_nop 0
	global_load_dwordx4 v[36:39], v[36:37], off offset:2112
	s_nop 0
	global_load_dwordx4 v[52:55], v[44:45], off
	global_load_dwordx4 v[48:51], v[44:45], off offset:64
	v_mov_b32_e32 v59, v1
	global_load_dwordx4 v[44:47], v56, vcc
	s_add_u32 vcc_lo, s46, s64
	v_lshlrev_b64 v[66:67], 1, v[58:59]
	s_addc_u32 vcc_hi, s47, s65
	v_lshl_add_u64 v[64:65], vcc, 0, v[66:67]
	v_add_co_u32_e32 v94, vcc, 0xc200000, v64
	s_cmp_eq_u32 s55, 0
	s_nop 0
	v_addc_co_u32_e32 v95, vcc, 0, v65, vcc
	global_load_dwordx4 v[56:59], v56, s[4:5]
	s_nop 0
	global_load_ushort v94, v[94:95], off offset:3392
	s_cbranch_scc1 .LBB0_837
	v_add_co_u32_e32 v96, vcc, 0xc1ff000, v64
	s_nop 1
	v_addc_co_u32_e32 v97, vcc, 0, v65, vcc
	global_load_ushort v95, v[96:97], off offset:2368
	s_branch .LBB0_838

; #define LAS __attribute__((address_space(3)))
; __device__ __forceinline__ unsigned pk2(float lo, float hi) { f32x2 v = {lo, hi}; bf16x2_t b = __builtin_convertvector(v, bf16x2_t); return __builtin_bit_cast(unsigned, b); }
; #define MFMA16(a, b, c) __builtin_amdgcn_mfma_f32_16x16x32_bf16((a), (b), (c), 0, 0, 0)
; __device__ __forceinline__ void rwkv_chunked_bh(const Ctx& F, int b, int h) {
;     ...
; #pragma unroll
;             for (int j = 0; j < 4; ++j) { const int t = c * 32 + w + 8 * j; const size_t row = (size_t)b * S + t; const bf16_t* p = proj + row * IN_EVEN_P + RW_OFF + 1024 + h * 64; const unsigned ul = ulane;
;                 cur.pv0[j] = p[ul]; cur.pv1[j] = t > 0 ? (p - IN_EVEN_P)[ul] : (bf16_t)0; cur.gq[j] = (LO + row * 1536 + 1024 + h * 64)[ul]; cur.bon[j] = *(const float*)(X + RX_BON + 4 * (w + 8 * j)); }
; #pragma unroll
;             for (int q = 0; q < 2; ++q) *(LAS u32x2*)(Ls + RB_SB + (16 * vt + i) * 144 + (16 * (2 * kh + q) + 4 * g) * 2) = (u32x2){pk2(sT[q][0], sT[q][1]), pk2(sT[q][2], sT[q][3])};
;             __syncthreads();
;             const bf16x8 bs0 = lds16(Ls + RB_SB + (16 * vt + i) * 144 + (8 * g) * 2), bs1 = lds16(Ls + RB_SB + (16 * vt + i) * 144 + (32 + 8 * g) * 2);
;             f32x4 y = MFMA16(qf[0], bs0, ((f32x4){0.f, 0.f, 0.f, 0.f})); y = MFMA16(qf[1], bs1, y); y = MFMA16(wyf, vf, y);
; #pragma unroll
;             for (int q = 0; q < 2; ++q) { f32x4 a = sT[q] * c4[q]; a = MFMA16(ng[q][0], bs0, a); a = MFMA16(ng[q][1], bs1, a); sT[q] = MFMA16(hf[q], vf, a); }
; #pragma unroll
;             for (int r = 0; r < 4; ++r) *(LAS float*)(Ls + RB_YL + ((16 * kh + 4 * g + r) * 64 + 16 * vt + i) * 4) = y[r];
;             if (cc > 0) rwkv_post_chunk(Y, L + ((cc - 1) & 1) * RBSTG + RB_YL, prv, b, h, c - 1, w, lane, mu_v, ln_w, ln_b);
.LBB0_838:
	s_bitcmp1_b32 s23, 0
	s_cselect_b32 s52, 0x4400, 0
	s_add_u32 s4, s46, s66
	s_addc_u32 s5, s47, s67
	v_lshl_add_u64 v[66:67], s[4:5], 0, v[66:67]
	v_add_co_u32_e32 v102, vcc, 0x32200000, v66
	s_add_u32 s4, s46, s6
	s_nop 0
	v_addc_co_u32_e32 v103, vcc, 0, v67, vcc
	v_add_co_u32_e32 v110, vcc, 0xc20a000, v64
	s_addc_u32 s5, s47, s7
	s_nop 0
	v_addc_co_u32_e32 v111, vcc, 0, v65, vcc
	v_add_co_u32_e32 v112, vcc, 0xc209000, v64
	s_nop 1
	v_addc_co_u32_e32 v113, vcc, 0, v65, vcc
	v_add_co_u32_e32 v114, vcc, 0x32206000, v66
	s_nop 1
	v_addc_co_u32_e32 v115, vcc, 0, v67, vcc
	v_add_co_u32_e32 v96, vcc, 0xc214000, v64
	s_nop 1
	v_addc_co_u32_e32 v97, vcc, 0, v65, vcc
	v_add_co_u32_e32 v100, vcc, 0xc213000, v64
	s_nop 1
	v_addc_co_u32_e32 v101, vcc, 0, v65, vcc
	v_add_co_u32_e32 v116, vcc, 0x3220c000, v66
	s_nop 1
	v_addc_co_u32_e32 v117, vcc, 0, v67, vcc
	v_add_co_u32_e32 v118, vcc, 0xc21e000, v64
	s_nop 1
	v_addc_co_u32_e32 v119, vcc, 0, v65, vcc
	v_add_co_u32_e32 v64, vcc, 0xc21d000, v64
	s_nop 1
	v_addc_co_u32_e32 v65, vcc, 0, v65, vcc
	v_add_co_u32_e32 v120, vcc, 0x32212000, v66
	s_nop 1
	v_addc_co_u32_e32 v121, vcc, 0, v67, vcc
	global_load_ushort v99, v[96:97], off offset:3392
	s_nop 0
	global_load_ushort v96, v[100:101], off offset:2368
	global_load_ushort v67, v[116:117], off offset:2048
	s_nop 0
	global_load_ushort v100, v[118:119], off offset:3392
	global_load_ushort v97, v[64:65], off offset:2368
	global_load_ushort v98, v[120:121], off offset:2048
	global_load_ushort v101, v[102:103], off offset:2048
	global_load_dword v61, v68, s[4:5] offset:2304
	global_load_ushort v104, v[110:111], off offset:3392
	s_nop 0
	global_load_ushort v103, v[112:113], off offset:2368
	global_load_ushort v102, v[114:115], off offset:2048
	global_load_dword v64, v68, s[4:5] offset:2336
	global_load_dword v65, v68, s[4:5] offset:2368
	global_load_dword v66, v68, s[4:5] offset:2400
	s_add_i32 s4, s52, 0
	v_add_u32_e32 v0, s4, v77
	v_add3_u32 v109, v0, v78, s80
	v_cvt_pk_bf16_f32 v110, v4, v5
	v_cvt_pk_bf16_f32 v111, v6, v7
	v_cvt_pk_bf16_f32 v112, v8, v9
	v_cvt_pk_bf16_f32 v113, v10, v11
	v_add_u32_e32 v0, v0, v60
	ds_write2_b64 v109, v[110:111], v[112:113] offset1:4
	s_waitcnt lgkmcnt(0)
	s_barrier
	ds_read_b128 v[110:113], v0
	ds_read_b128 v[114:117], v0 offset:64
	s_waitcnt vmcnt(20)
	v_pk_mul_f32 v[6:7], v[6:7], v[42:43]
	v_pk_mul_f32 v[4:5], v[4:5], v[40:41]
	s_waitcnt vmcnt(19)
	v_pk_mul_f32 v[10:11], v[10:11], v[38:39]
	v_pk_mul_f32 v[8:9], v[8:9], v[36:37]
	s_waitcnt vmcnt(18) lgkmcnt(1)
	v_mfma_f32_16x16x32_bf16 v[52:55], v[52:55], v[110:113], 0
	s_add_i32 s4, s4, s88
	v_add3_u32 v0, s4, v79, v81
	s_cmp_eq_u32 s23, 0
	v_mfma_f32_16x16x32_bf16 v[4:7], v[12:15], v[110:113], v[4:7]
	v_mfma_f32_16x16x32_bf16 v[8:11], v[20:23], v[110:113], v[8:11]
	s_waitcnt vmcnt(17) lgkmcnt(0)
	v_mfma_f32_16x16x32_bf16 v[48:51], v[48:51], v[114:117], v[52:55]
	v_mfma_f32_16x16x32_bf16 v[4:7], v[16:19], v[114:117], v[4:7]
	v_mfma_f32_16x16x32_bf16 v[8:11], v[24:27], v[114:117], v[8:11]
	s_waitcnt vmcnt(16)
	v_mfma_f32_16x16x32_bf16 v[4:7], v[32:35], v[44:47], v[4:7]
	v_mfma_f32_16x16x32_bf16 v[8:11], v[28:31], v[44:47], v[8:11]
	s_waitcnt vmcnt(15)
	v_mfma_f32_16x16x32_bf16 v[12:15], v[56:59], v[44:47], v[48:51]
	s_nop 7
	ds_write2st64_b32 v0, v12, v13 offset0:36 offset1:37
	ds_write2st64_b32 v0, v14, v15 offset0:38 offset1:39
	s_cbranch_scc1 .LBB0_840
	s_andn2_b32 s4, 1, s23
	s_mulk_i32 s4, 0x4400
	v_add_u32_e32 v13, s4, v80
	v_mov_b32_e32 v0, v71
	v_add_u32_e32 v12, s81, v13
	ds_read_b32 v12, v12 offset:9216
	v_add_u32_e32 v14, s83, v13
	v_add_u32_e32 v15, s85, v13
	v_add_u32_e32 v13, s87, v13
	ds_read_b32 v18, v14 offset:9216
	ds_read_b32 v15, v15 offset:9216
	ds_read_b32 v14, v13 offset:9216
	s_waitcnt lgkmcnt(3)
	v_add_f32_dpp v13, v12, v12 quad_perm:[1,0,3,2] row_mask:0xf bank_mask:0xf bound_ctrl:1
	s_nop 1
	v_add_f32_dpp v13, v13, v13 quad_perm:[2,3,0,1] row_mask:0xf bank_mask:0xf bound_ctrl:1
	s_nop 1
	v_add_f32_dpp v13, v13, v13 row_half_mirror row_mask:0xf bank_mask:0xf bound_ctrl:1
	s_nop 1
	v_add_f32_dpp v13, v13, v13 row_mirror row_mask:0xf bank_mask:0xf bound_ctrl:1
	s_nop 0
	v_readlane_b32 s5, v13, 16
	v_readlane_b32 s4, v13, 0
	s_nop 0
	v_mov_b32_e32 v16, s5
	v_readlane_b32 s5, v13, 48
	v_add_f32_e32 v16, s4, v16
	v_readlane_b32 s4, v13, 32
	v_mov_b32_e32 v13, s5
	s_nop 0
	v_add_f32_e32 v13, s4, v13
	v_add_f32_e32 v13, v16, v13
	v_mul_f32_e32 v16, v12, v12
	s_nop 1
	v_mov_b32_dpp v16, v16 quad_perm:[1,0,3,2] row_mask:0xf bank_mask:0xf bound_ctrl:1
	v_fmac_f32_e32 v16, v12, v12
	v_fmac_f32_e32 v12, 0xbc800000, v13
	s_nop 0
	v_add_f32_dpp v16, v16, v16 quad_perm:[2,3,0,1] row_mask:0xf bank_mask:0xf bound_ctrl:1
	s_nop 1
	v_add_f32_dpp v16, v16, v16 row_half_mirror row_mask:0xf bank_mask:0xf bound_ctrl:1
	s_nop 1
	v_add_f32_dpp v16, v16, v16 row_mirror row_mask:0xf bank_mask:0xf bound_ctrl:1
	s_nop 0
	v_readlane_b32 s5, v16, 16
	v_readlane_b32 s4, v16, 0
	s_nop 0
	v_mov_b32_e32 v17, s5
	v_readlane_b32 s5, v16, 48
	v_add_f32_e32 v17, s4, v17
	v_readlane_b32 s4, v16, 32
	v_mov_b32_e32 v16, s5
	s_nop 0
	v_add_f32_e32 v16, s4, v16
	v_add_f32_e32 v16, v17, v16
	v_mul_f32_e32 v17, 0x3c800000, v13
	v_mul_f32_e32 v17, v17, v17
	v_fma_f32 v16, v16, s90, -v17
	v_max_f32_e32 v16, 0, v16
	v_add_f32_e32 v16, 0x3a27c5ac, v16
	v_rsq_f32_e32 v250, v16
	s_add_u32 s4, s46, s68
	v_mov_b32_e32 v13, v250
	v_mul_f32_e32 v12, v12, v13
	v_lshlrev_b32_e32 v13, 16, v91
	v_lshlrev_b32_e32 v16, 16, v92
	v_sub_f32_e32 v16, v16, v13
	v_fma_f32 v12, v73, v12, v74
	v_fmac_f32_e32 v13, v72, v16
	v_fmac_f32_e32 v12, v13, v108
	v_lshlrev_b32_e32 v13, 16, v93
	v_mul_f32_e32 v12, v12, v13
	v_cvt_pk_bf16_f32 v19, v12, s0
	s_waitcnt lgkmcnt(2)
; #define LAS __attribute__((address_space(3)))
; __device__ __forceinline__ float bf2f(bf16_t v) { return __uint_as_float(((unsigned)v) << 16); }
; __device__ __forceinline__ bf16_t f2bf(float f) { return (bf16_t)(pk2(f, 0.f) & 0xffffu); }
; __device__ __forceinline__ float wave_sum_fast(float x) { x = reduce16(x); return (rl_(x, 0) + rl_(x, 16)) + (rl_(x, 32) + rl_(x, 48)); }
; __device__ __forceinline__ unsigned launder_(unsigned x) { asm volatile("" : "+v"(x)); return x; }
; __device__ __forceinline__ void rwkv_post_chunk(bf16_t* Y, const LAS unsigned char* Yp, const RwkvPostIn& in, int b, int h, int c, int w, int lane, float mu_v, float ln_w, float ln_b) {
;     const unsigned ulane = launder_((unsigned)lane);
; #pragma unroll
;     for (int j = 0; j < 4; ++j) {
;         const int tl = w + 8 * j; const size_t row = (size_t)b * S + c * 32 + tl;
;         const float yv = *(const LAS float*)(Yp + (tl * 64 + lane) * 4);
;         const float s1 = wave_sum_fast(yv), s2 = wave_sum_fast(yv * yv);
;         const float mean = s1 * (1.0f / 64.f), var = fmaxf(s2 * (1.0f / 64.f) - mean * mean, 0.f);
;         const float yn = (yv - mean) * (1.0f / sqrtf(var + 64e-5f)) * ln_w + ln_b;
;         float v = bf2f(in.pv0[j]); v += (bf2f(in.pv1[j]) - v) * mu_v;
;         (Y + row * D + 512 + h * 64)[ulane] = f2bf((yn + in.bon[j] * v) * bf2f(in.gq[j]));
;     }
	v_add_f32_dpp v12, v18, v18 quad_perm:[1,0,3,2] row_mask:0xf bank_mask:0xf bound_ctrl:1
	s_nop 1
	v_add_f32_dpp v12, v12, v12 quad_perm:[2,3,0,1] row_mask:0xf bank_mask:0xf bound_ctrl:1
	s_nop 1
	v_add_f32_dpp v12, v12, v12 row_half_mirror row_mask:0xf bank_mask:0xf bound_ctrl:1
	s_nop 1
	v_add_f32_dpp v12, v12, v12 row_mirror row_mask:0xf bank_mask:0xf bound_ctrl:1
	s_nop 0
	v_readlane_b32 s52, v12, 16
	v_readlane_b32 s5, v12, 0
	s_nop 0
	v_mov_b32_e32 v13, s52
	v_readlane_b32 s52, v12, 48
	v_add_f32_e32 v13, s5, v13
	v_readlane_b32 s5, v12, 32
	v_mov_b32_e32 v12, s52
	s_nop 0
	v_add_f32_e32 v12, s5, v12
	v_add_f32_e32 v20, v13, v12
	v_mul_f32_e32 v12, v18, v18
	s_nop 1
	v_mov_b32_dpp v12, v12 quad_perm:[1,0,3,2] row_mask:0xf bank_mask:0xf bound_ctrl:1
	v_fmac_f32_e32 v12, v18, v18
	v_fmac_f32_e32 v18, 0xbc800000, v20
	s_nop 0
	v_add_f32_dpp v12, v12, v12 quad_perm:[2,3,0,1] row_mask:0xf bank_mask:0xf bound_ctrl:1
	s_nop 1
	v_add_f32_dpp v12, v12, v12 row_half_mirror row_mask:0xf bank_mask:0xf bound_ctrl:1
	s_nop 1
	v_add_f32_dpp v12, v12, v12 row_mirror row_mask:0xf bank_mask:0xf bound_ctrl:1
	s_nop 0
	v_readlane_b32 s52, v12, 16
	v_readlane_b32 s5, v12, 0
	s_nop 0
	v_mov_b32_e32 v13, s52
	v_readlane_b32 s52, v12, 48
	v_add_f32_e32 v13, s5, v13
	v_readlane_b32 s5, v12, 32
	v_mov_b32_e32 v12, s52
	s_mov_b32 s52, 0x41f0000
	v_add_f32_e32 v12, s5, v12
	v_add_f32_e32 v12, v13, v12
	v_mul_f32_e32 v13, 0x3c800000, v20
	v_mul_f32_e32 v13, v13, v13
	v_fma_f32 v12, v12, s90, -v13
	v_max_f32_e32 v12, 0, v12
	v_add_f32_e32 v12, 0x3a27c5ac, v12
	v_rsq_f32_e32 v251, v12
	s_addc_u32 s5, s47, s69
	s_nop 0
	v_lshl_add_u64 v[12:13], v[0:1], 1, s[4:5]
	v_add_co_u32_e32 v16, vcc, s52, v12
	s_mov_b32 s52, 0x41f4000
	s_nop 0
	v_addc_co_u32_e32 v17, vcc, 0, v13, vcc
	global_store_short v[16:17], v19, off offset:1024
	v_mov_b32_e32 v0, v251
	v_lshlrev_b32_e32 v16, 16, v88
	v_lshlrev_b32_e32 v17, 16, v89
	v_sub_f32_e32 v17, v17, v16
	v_fmac_f32_e32 v16, v72, v17
	v_mul_f32_e32 v0, v18, v0
	s_waitcnt lgkmcnt(1)
	v_add_f32_dpp v17, v15, v15 quad_perm:[1,0,3,2] row_mask:0xf bank_mask:0xf bound_ctrl:1
	v_fma_f32 v0, v73, v0, v74
	v_fmac_f32_e32 v0, v16, v107
	v_add_f32_dpp v17, v17, v17 quad_perm:[2,3,0,1] row_mask:0xf bank_mask:0xf bound_ctrl:1
	v_lshlrev_b32_e32 v16, 16, v90
	v_mul_f32_e32 v0, v0, v16
	v_add_f32_dpp v17, v17, v17 row_half_mirror row_mask:0xf bank_mask:0xf bound_ctrl:1
	v_cvt_pk_bf16_f32 v0, v0, s0
	s_nop 0
	v_add_f32_dpp v17, v17, v17 row_mirror row_mask:0xf bank_mask:0xf bound_ctrl:1
	s_nop 0
	v_readlane_b32 s5, v17, 16
	v_readlane_b32 s4, v17, 0
	s_nop 0
	v_mov_b32_e32 v18, s5
	v_readlane_b32 s5, v17, 48
	v_add_f32_e32 v18, s4, v18
	v_readlane_b32 s4, v17, 32
	v_mov_b32_e32 v17, s5
	s_nop 0
	v_add_f32_e32 v17, s4, v17
	v_add_f32_e32 v18, v18, v17
	v_mul_f32_e32 v17, v15, v15
	s_nop 1
	v_mov_b32_dpp v17, v17 quad_perm:[1,0,3,2] row_mask:0xf bank_mask:0xf bound_ctrl:1
	v_fmac_f32_e32 v17, v15, v15
	v_fmac_f32_e32 v15, 0xbc800000, v18
	s_nop 0
	v_add_f32_dpp v17, v17, v17 quad_perm:[2,3,0,1] row_mask:0xf bank_mask:0xf bound_ctrl:1
	s_nop 1
	v_add_f32_dpp v17, v17, v17 row_half_mirror row_mask:0xf bank_mask:0xf bound_ctrl:1
	s_nop 1
	v_add_f32_dpp v17, v17, v17 row_mirror row_mask:0xf bank_mask:0xf bound_ctrl:1
	s_nop 0
	v_readlane_b32 s5, v17, 16
	v_readlane_b32 s4, v17, 0
	s_nop 0
	v_mov_b32_e32 v19, s5
	v_readlane_b32 s5, v17, 48
	v_add_f32_e32 v19, s4, v19
	v_readlane_b32 s4, v17, 32
	v_mov_b32_e32 v17, s5
	s_nop 0
	v_add_f32_e32 v17, s4, v17
	v_add_f32_e32 v17, v19, v17
	v_mul_f32_e32 v19, 0x3c800000, v18
	v_mul_f32_e32 v19, v19, v19
	v_fma_f32 v17, v17, s90, -v19
	v_max_f32_e32 v17, 0, v17
	v_add_f32_e32 v17, 0x3a27c5ac, v17
	v_rsq_f32_e32 v252, v17
	v_add_co_u32_e32 v16, vcc, s52, v12
	s_mov_b32 s52, 0x41f8000
	s_nop 0
	v_addc_co_u32_e32 v17, vcc, 0, v13, vcc
	global_store_short v[16:17], v0, off offset:1024
	v_mov_b32_e32 v0, v252
	v_mul_f32_e32 v0, v15, v0
	v_lshlrev_b32_e32 v15, 16, v85
	v_lshlrev_b32_e32 v16, 16, v86
	v_sub_f32_e32 v16, v16, v15
	v_fmac_f32_e32 v15, v72, v16
	v_fma_f32 v0, v73, v0, v74
	s_waitcnt lgkmcnt(0)
	v_add_f32_dpp v16, v14, v14 quad_perm:[1,0,3,2] row_mask:0xf bank_mask:0xf bound_ctrl:1
	v_fmac_f32_e32 v0, v15, v106
	v_lshlrev_b32_e32 v15, 16, v87
	v_add_f32_dpp v16, v16, v16 quad_perm:[2,3,0,1] row_mask:0xf bank_mask:0xf bound_ctrl:1
	v_mul_f32_e32 v0, v0, v15
	v_cvt_pk_bf16_f32 v0, v0, s0
	v_add_f32_dpp v16, v16, v16 row_half_mirror row_mask:0xf bank_mask:0xf bound_ctrl:1
	s_nop 1
	v_add_f32_dpp v16, v16, v16 row_mirror row_mask:0xf bank_mask:0xf bound_ctrl:1
	s_nop 0
	v_readlane_b32 s5, v16, 16
	v_readlane_b32 s4, v16, 0
	s_nop 0
	v_mov_b32_e32 v17, s5
	v_readlane_b32 s5, v16, 48
	v_add_f32_e32 v17, s4, v17
	v_readlane_b32 s4, v16, 32
	v_mov_b32_e32 v16, s5
	s_nop 0
	v_add_f32_e32 v16, s4, v16
	v_add_f32_e32 v18, v17, v16
	v_mul_f32_e32 v16, v14, v14
	s_nop 1
	v_mov_b32_dpp v16, v16 quad_perm:[1,0,3,2] row_mask:0xf bank_mask:0xf bound_ctrl:1
	v_fmac_f32_e32 v16, v14, v14
	v_fmac_f32_e32 v14, 0xbc800000, v18
	s_nop 0
	v_add_f32_dpp v16, v16, v16 quad_perm:[2,3,0,1] row_mask:0xf bank_mask:0xf bound_ctrl:1
	s_nop 1
	v_add_f32_dpp v16, v16, v16 row_half_mirror row_mask:0xf bank_mask:0xf bound_ctrl:1
	s_nop 1
	v_add_f32_dpp v16, v16, v16 row_mirror row_mask:0xf bank_mask:0xf bound_ctrl:1
	s_nop 0
	v_readlane_b32 s5, v16, 16
	v_readlane_b32 s4, v16, 0
	s_nop 0
	v_mov_b32_e32 v17, s5
	v_readlane_b32 s5, v16, 48
	v_add_f32_e32 v17, s4, v17
	v_readlane_b32 s4, v16, 32
	v_mov_b32_e32 v16, s5
	s_nop 0
	v_add_f32_e32 v16, s4, v16
	v_add_f32_e32 v16, v17, v16
	v_mul_f32_e32 v17, 0x3c800000, v18
	v_mul_f32_e32 v17, v17, v17
	v_fma_f32 v16, v16, s90, -v17
	v_max_f32_e32 v16, 0, v16
	v_add_f32_e32 v16, 0x3a27c5ac, v16
	v_rsq_f32_e32 v253, v16
	v_add_co_u32_e32 v16, vcc, s52, v12
	s_nop 1
	v_addc_co_u32_e32 v17, vcc, 0, v13, vcc
	global_store_short v[16:17], v0, off offset:1024
	v_mov_b32_e32 v0, v253
	v_mul_f32_e32 v0, v14, v0
	v_lshlrev_b32_e32 v14, 16, v82
	v_lshlrev_b32_e32 v15, 16, v83
	v_sub_f32_e32 v15, v15, v14
	v_fma_f32 v0, v73, v0, v74
	v_fmac_f32_e32 v14, v72, v15
	v_fmac_f32_e32 v0, v14, v105
	v_lshlrev_b32_e32 v14, 16, v84
	v_mul_f32_e32 v0, v0, v14
	v_add_co_u32_e32 v12, vcc, 0x41fc000, v12
	v_cvt_pk_bf16_f32 v0, v0, s0
	s_nop 0
	v_addc_co_u32_e32 v13, vcc, 0, v13, vcc
	global_store_short v[12:13], v0, off offset:1024
	s_branch .Lrw_latch_st

; __device__ __forceinline__ void rwkv_chunked_bh(const Ctx& F, int b, int h) {
;     ...
;         for (int cc = 0; cc < RG; ++cc) {
;             const int c = grp * RG + cc; const unsigned char* X = XS + cc * RX_BYTES;
;             LAS unsigned char* const Ls = L + (cc & 1) * RBSTG;
;             bf16x8 ng[2][2], hf[2], qf[2], wyf, vf; f32x4 c4[2];
;             const unsigned o128 = launder_((unsigned)(i * 128 + 16 * g)), o64 = launder_((unsigned)(i * 64 + 16 * g)), ulane = launder_((unsigned)lane);
; #pragma unroll
;             for (int q = 0; q < 2; ++q) { const int kt = 2 * kh + q;
;                 ng[q][0] = glb16(X + RX_NGT + 16 * kt * 128 + o128); ng[q][1] = glb16(X + RX_NGT + 16 * kt * 128 + 64 + o128);
;                 hf[q] = glb16(X + RX_HT + 16 * kt * 64 + o64); c4[q] = *(const f32x4*)(X + RX_CC + 16 * kt * 4 + (unsigned)(16 * g)); }
;             qf[0] = glb16(X + RX_QT + 16 * kh * 128 + o128); qf[1] = glb16(X + RX_QT + 16 * kh * 128 + 64 + o128);
;             wyf = glb16(X + RX_WYT + 16 * kh * 64 + o64); vf = glb16(X + RX_VT + 16 * vt * 64 + o64);
;             RwkvPostIn cur;
; #pragma unroll
;             for (int j = 0; j < 4; ++j) { const int t = c * 32 + w + 8 * j; const size_t row = (size_t)b * S + t; const bf16_t* p = proj + row * IN_EVEN_P + RW_OFF + 1024 + h * 64; const unsigned ul = ulane;
;                 cur.pv0[j] = p[ul]; cur.pv1[j] = t > 0 ? (p - IN_EVEN_P)[ul] : (bf16_t)0; cur.gq[j] = (LO + row * 1536 + 1024 + h * 64)[ul]; cur.bon[j] = *(const float*)(X + RX_BON + 4 * (w + 8 * j)); }
; #pragma unroll
;             for (int q = 0; q < 2; ++q) *(LAS u32x2*)(Ls + RB_SB + (16 * vt + i) * 144 + (16 * (2 * kh + q) + 4 * g) * 2) = (u32x2){pk2(sT[q][0], sT[q][1]), pk2(sT[q][2], sT[q][3])};
;             __syncthreads();
;             const bf16x8 bs0 = lds16(Ls + RB_SB + (16 * vt + i) * 144 + (8 * g) * 2), bs1 = lds16(Ls + RB_SB + (16 * vt + i) * 144 + (32 + 8 * g) * 2);
;             f32x4 y = MFMA16(qf[0], bs0, ((f32x4){0.f, 0.f, 0.f, 0.f})); y = MFMA16(qf[1], bs1, y); y = MFMA16(wyf, vf, y);
; #pragma unroll
;             for (int q = 0; q < 2; ++q) { f32x4 a = sT[q] * c4[q]; a = MFMA16(ng[q][0], bs0, a); a = MFMA16(ng[q][1], bs1, a); sT[q] = MFMA16(hf[q], vf, a); }
; #pragma unroll
;             for (int r = 0; r < 4; ++r) *(LAS float*)(Ls + RB_YL + ((16 * kh + 4 * g + r) * 64 + 16 * vt + i) * 4) = y[r];
.Lrw_latch_st:
	s_add_i32 s23, s23, 1
	s_add_u32 s68, s68, 0x10000
	s_addc_u32 s69, s69, 0
	s_add_i32 s55, s55, 32
	s_add_u32 s66, s66, 0x18000
	s_addc_u32 s67, s67, 0
	s_add_u32 s64, s64, 0x28000
	s_addc_u32 s65, s65, 0
	s_add_u32 s62, s62, 0x5a00
	s_addc_u32 s63, s63, 0
	s_add_u32 s60, s60, 0x5a00
	s_addc_u32 s61, s61, 0
	s_add_u32 s10, s10, 0x5a00
	s_addc_u32 s11, s11, 0
	s_add_u32 s8, s8, 0x5a00
	s_addc_u32 s9, s9, 0
	s_add_u32 s6, s6, 0x5a00
	s_addc_u32 s7, s7, 0
	s_mov_b64 s[4:5], 0x5a00
	s_cmp_eq_u32 s23, 4
	v_lshl_add_u64 v[2:3], v[2:3], 0, s[4:5]
	s_cbranch_scc1 .LBB0_791
	s_waitcnt vmcnt(18)
	v_mov_b32_e32 v91, v94
	s_waitcnt vmcnt(9)
	v_mov_b32_e32 v88, v104
	v_mov_b32_e32 v85, v99
	v_mov_b32_e32 v82, v100
	v_mov_b32_e32 v92, v95
	s_waitcnt vmcnt(8)
	v_mov_b32_e32 v89, v103
	v_mov_b32_e32 v86, v96
	v_mov_b32_e32 v83, v97
	v_mov_b32_e32 v93, v101
	s_waitcnt vmcnt(7)
	v_mov_b32_e32 v90, v102
	v_mov_b32_e32 v87, v67
	v_mov_b32_e32 v84, v98
	v_mov_b32_e32 v108, v61
	s_waitcnt vmcnt(6)
	v_mov_b32_e32 v107, v64
	s_waitcnt vmcnt(5)
	v_mov_b32_e32 v106, v65
	s_waitcnt vmcnt(4)
	v_mov_b32_e32 v105, v66
	s_branch .Lrw_top2
